# P1/P8 last-unit epilogue: wave 1 warms the 32 KiB of code after the GEMM part (copy code + grid-barrier protocol code), stacked on v93
# baseline (speedup 1.0000x reference)
.LBB0_204:
	v_cndmask_b32_e64 v140, 0, 1, s[4:5]
	s_and_b32 s2, s53, 1
	v_mov_b32_e32 v150, v143
	v_mov_b32_e32 v141, v1
	v_cmp_ne_u32_e64 s[6:7], 1, v140
	s_cmp_eq_u64 s[4:5], 0
	s_cbranch_scc1 .Lcpf_skip_w0
	v_readlane_b32 s98, v254, 61
	s_cmp_lg_u32 s98, 1
	s_cbranch_scc1 .Lcpf_skip_w0
	s_getpc_b64 s[98:99]

.Lcpf_skip_w0:
	s_cmp_lg_u64 s[4:5], 0
	s_cselect_b32 s98, 1, 0
	s_andn2_b64 vcc, exec, s[4:5]
	s_mov_b64 s[4:5], -1
	s_cbranch_vccnz .LBB0_206
	s_lshl_b32 s3, s2, 12
	s_mov_b64 s[4:5], 0

.LBB0_1721:
	v_cndmask_b32_e64 v140, 0, 1, s[4:5]
	s_and_b32 s3, s85, 1
	v_mov_b32_e32 v141, v1
	v_mov_b32_e32 v150, v143
	v_cmp_ne_u32_e64 s[6:7], 1, v140
	s_cmp_eq_u64 s[4:5], 0
	s_cbranch_scc1 .Lcpf_skip_w1
	v_readlane_b32 s98, v254, 61
	s_cmp_lg_u32 s98, 1
	s_cbranch_scc1 .Lcpf_skip_w1
	s_getpc_b64 s[98:99]

.Lcpf_skip_w1:
	s_cmp_lg_u64 s[4:5], 0
	s_cselect_b32 s98, 1, 0
	s_andn2_b64 vcc, exec, s[4:5]
	s_mov_b64 s[4:5], -1
	s_cbranch_vccnz .LBB0_1723
	s_lshl_b32 s12, s3, 12
	s_mov_b64 s[4:5], 0
